# selected/window attention row-max across the four 16-lane rows via v_permlane16/32_swap + max instead of two ds_bpermute LDS round trips
# baseline (speedup 1.0000x reference)
; DI float quad_max(float v) { v = fmaxf(v, __shfl_xor(v, 16)); v = fmaxf(v, __shfl_xor(v, 32)); return v; }
; DI void softmax_tile_full(f32x4 (&st)[4], float& m, float& l, f32x4 (&ot)[4]) {
;   float tm = st[0][0];
; #pragma unroll
;   for (int mt = 0; mt < 4; ++mt)
; #pragma unroll
;     for (int j = 0; j < 4; ++j) tm = fmaxf(tm, st[mt][j]);
;   tm = quad_max(tm) * 0.125f;
;   const float mn = fmaxf(m, tm);
;   const float alpha = __expf(m - mn);
;   float ps = 0.f;
; #pragma unroll
;   for (int mt = 0; mt < 4; ++mt)
; #pragma unroll
;     for (int j = 0; j < 4; ++j) { const float p = __expf(st[mt][j] * 0.125f - mn); st[mt][j] = p; ps += p; }
;   l = l * alpha + ps;
;   m = mn;
; #pragma unroll
;   for (int dt = 0; dt < 4; ++dt)
; #pragma unroll
;     for (int j = 0; j < 4; ++j) ot[dt][j] *= alpha;
; }
; DI void sel_attn_item(const Params& P, int it, u16* sQ, u16* sKunused, u16* sVunused) {
;     ...
; #pragma unroll
;     for (int qt = 0; qt < 2; ++qt) {
;       f32x4 st[4];
;       st_mma(st, sK, bq[qt], lane);
;       const bool selq = (mysel[qt] >> kb) & 1ull;
;       if (__ballot(selq) == ~0ull && kb * 64 + 63 <= t0 + 16 * qt) softmax_tile_full(st, m[qt], lsum[qt], ot[qt]);
.LBB0_246:
	v_add_u32_e32 v5, 0x7000, v211
	ds_read_b128 v[124:127], v173 offset:18432
	ds_read_b128 v[128:131], v173 offset:18496
	ds_read_b128 v[132:135], v173 offset:20736
	ds_read_b128 v[136:139], v173 offset:20800
	ds_read_b128 v[140:143], v173 offset:23040
	ds_read_b128 v[120:123], v173 offset:23104
	ds_read_b128 v[116:119], v210 offset:18432
	ds_read_b128 v[112:115], v210 offset:18496
	ds_read2_b64 v[0:3], v5 offset0:160 offset1:164
	s_waitcnt lgkmcnt(8)
	v_mfma_f32_16x16x32_bf16 v[6:9], v[124:127], v[48:51], 0
	v_add_u32_e32 v15, 0x6800, v212
	v_lshlrev_b64 v[180:181], v4, 1
	v_add_u32_e32 v14, 0x6800, v211
	s_waitcnt lgkmcnt(0)
	v_mov_b64_e32 v[104:105], v[2:3]
	v_mov_b64_e32 v[106:107], v[0:1]
	ds_read2_b64 v[0:3], v5 offset0:168 offset1:172
	v_mfma_f32_16x16x32_bf16 v[156:159], v[128:131], v[52:55], v[6:9]
	v_add_u32_e32 v80, 0x7800, v211
	ds_read2_b64 v[108:111], v14 offset0:128 offset1:132
	ds_read2_b64 v[100:103], v80 offset0:200 offset1:204
	ds_read2_b64 v[6:9], v15 offset0:136 offset1:140
	v_mfma_f32_16x16x32_bf16 v[10:13], v[132:135], v[48:51], 0
	s_waitcnt lgkmcnt(3)
	v_mov_b64_e32 v[88:89], v[2:3]
	v_mov_b64_e32 v[90:91], v[0:1]
	v_lshlrev_b32_e32 v222, 6, v4
	v_mfma_f32_16x16x32_bf16 v[0:3], v[116:119], v[48:51], 0
	s_waitcnt lgkmcnt(0)
	v_mov_b64_e32 v[96:97], v[8:9]
	v_mov_b64_e32 v[98:99], v[6:7]
	v_or_b32_e32 v233, 63, v222
	v_mfma_f32_16x16x32_bf16 v[6:9], v[140:143], v[48:51], 0
	v_cmp_gt_i32_e32 vcc, v233, v170
	v_mfma_f32_16x16x32_bf16 v[152:155], v[136:139], v[52:55], v[10:13]
	ds_read2_b64 v[92:95], v14 offset0:136 offset1:140
	s_nop 1
	ds_read2_b64 v[10:13], v15 offset0:128 offset1:132
	ds_read2_b64 v[84:87], v80 offset0:192 offset1:196
	s_waitcnt lgkmcnt(1)
	v_mov_b64_e32 v[82:83], v[10:11]
	v_mfma_f32_16x16x32_bf16 v[144:147], v[112:115], v[52:55], v[0:3]
	v_mov_b64_e32 v[80:81], v[12:13]
	s_nop 1
	v_and_b32_e32 v1, v181, v175
	v_and_b32_e32 v0, v180, v174
	v_cmp_ne_u64_e64 s[0:1], 0, v[0:1]
	v_mfma_f32_16x16x32_bf16 v[148:151], v[120:123], v[52:55], v[6:9]
	s_cmp_lg_u64 s[0:1], -1
	s_cselect_b64 s[2:3], -1, 0
	s_or_b64 s[4:5], s[2:3], vcc
	s_mov_b64 s[2:3], -1
	s_and_b64 vcc, exec, s[4:5]
	s_cbranch_vccnz .LBB0_248
	v_max_f32_e32 v0, v157, v157
	v_max_f32_e32 v1, v156, v156
	v_max_f32_e32 v0, v1, v0
	v_max3_f32 v0, v0, v158, v159
	v_max3_f32 v0, v0, v152, v153
	v_mbcnt_hi_u32_b32 v1, -1, v184
	v_max3_f32 v0, v0, v154, v155
	v_and_b32_e32 v3, 64, v1
	v_max3_f32 v0, v0, v148, v149
	v_xor_b32_e32 v2, 16, v1
	v_add_u32_e32 v3, 64, v3
	v_max3_f32 v0, v0, v150, v151
	v_cmp_lt_i32_e32 vcc, v2, v3
	v_max3_f32 v0, v0, v144, v145
	v_max3_f32 v0, v0, v146, v147
	v_cndmask_b32_e32 v2, v1, v2, vcc
	v_lshlrev_b32_e32 v2, 2, v2
	v_mov_b32_e32 v2, v0
	v_mov_b32_e32 v254, v0
	s_nop 1
	v_permlane16_swap_b32_e32 v2, v254
	s_nop 0
	v_max_f32_e32 v2, v2, v254
	s_mov_b64 s[2:3], 0
	s_waitcnt lgkmcnt(0)
	v_max_f32_e32 v2, v2, v2
	v_max_f32_e32 v0, v0, v2
	v_xor_b32_e32 v2, 32, v1
	v_cmp_lt_i32_e32 vcc, v2, v3
	s_nop 1
	v_cndmask_b32_e32 v1, v1, v2, vcc
	v_lshlrev_b32_e32 v1, 2, v1
	v_mov_b32_e32 v1, v0
	v_mov_b32_e32 v254, v0
	s_nop 1
	v_permlane32_swap_b32_e32 v1, v254
	s_nop 0
	v_max_f32_e32 v1, v1, v254
	s_waitcnt lgkmcnt(0)
	v_max_f32_e32 v1, v1, v1
	v_max_f32_e32 v0, v0, v1
	v_mul_f32_e32 v0, 0x3e000000, v0
	v_max_f32_e32 v1, v221, v221
	v_max_f32_e32 v220, v1, v0
	v_fma_f32 v0, v156, s33, -v220
	v_mul_f32_e32 v0, 0x3fb8aa3b, v0
	v_fma_f32 v1, v157, s33, -v220
	v_exp_f32_e32 v0, v0
	v_mul_f32_e32 v1, 0x3fb8aa3b, v1
	v_fma_f32 v2, v158, s33, -v220
	v_exp_f32_e32 v1, v1
	v_mul_f32_e32 v2, 0x3fb8aa3b, v2
	v_fma_f32 v3, v159, s33, -v220
	v_exp_f32_e32 v2, v2
	v_mul_f32_e32 v3, 0x3fb8aa3b, v3
	v_exp_f32_e32 v3, v3
	v_add_f32_e32 v4, 0, v0
	v_add_f32_e32 v4, v1, v4
	v_add_f32_e32 v4, v2, v4
	v_add_f32_e32 v8, v3, v4
	v_fma_f32 v4, v152, s33, -v220
	v_mul_f32_e32 v4, 0x3fb8aa3b, v4
	v_fma_f32 v5, v153, s33, -v220
	v_exp_f32_e32 v4, v4
	v_mul_f32_e32 v5, 0x3fb8aa3b, v5
	v_fma_f32 v6, v154, s33, -v220
	v_exp_f32_e32 v5, v5
	v_mul_f32_e32 v6, 0x3fb8aa3b, v6
	v_fma_f32 v7, v155, s33, -v220
	v_exp_f32_e32 v6, v6
	v_mul_f32_e32 v7, 0x3fb8aa3b, v7
	v_exp_f32_e32 v7, v7
	v_add_f32_e32 v8, v4, v8
	v_add_f32_e32 v8, v5, v8
	v_add_f32_e32 v8, v6, v8
	v_add_f32_e32 v12, v7, v8
	v_fma_f32 v8, v148, s33, -v220
	v_mul_f32_e32 v8, 0x3fb8aa3b, v8
	v_fma_f32 v9, v149, s33, -v220
	v_exp_f32_e32 v8, v8
	v_mul_f32_e32 v9, 0x3fb8aa3b, v9
	v_fma_f32 v10, v150, s33, -v220
	v_exp_f32_e32 v9, v9
	v_mul_f32_e32 v10, 0x3fb8aa3b, v10
	v_fma_f32 v11, v151, s33, -v220
	v_exp_f32_e32 v10, v10
	v_mul_f32_e32 v11, 0x3fb8aa3b, v11
	v_exp_f32_e32 v11, v11
	v_add_f32_e32 v12, v8, v12
	v_add_f32_e32 v12, v9, v12
	v_add_f32_e32 v12, v10, v12
	v_add_f32_e32 v162, v11, v12
	v_fma_f32 v12, v144, s33, -v220
	v_mul_f32_e32 v12, 0x3fb8aa3b, v12
	v_fma_f32 v13, v145, s33, -v220
	v_exp_f32_e32 v12, v12
	v_mul_f32_e32 v13, 0x3fb8aa3b, v13
	v_fma_f32 v14, v146, s33, -v220
	v_exp_f32_e32 v13, v13
	v_mul_f32_e32 v14, 0x3fb8aa3b, v14
	v_fma_f32 v15, v147, s33, -v220
	v_exp_f32_e32 v14, v14
	v_mul_f32_e32 v15, 0x3fb8aa3b, v15
	v_exp_f32_e32 v15, v15
	v_add_f32_e32 v162, v12, v162
	v_add_f32_e32 v162, v13, v162
	v_add_f32_e32 v162, v14, v162
	v_add_f32_e32 v162, v15, v162
; DI float quad_max(float v) { v = fmaxf(v, __shfl_xor(v, 16)); v = fmaxf(v, __shfl_xor(v, 32)); return v; }
; DI void softmax_tile(f32x4 (&st)[4], const bool (&msk)[4][4], float& m, float& l, f32x4 (&ot)[4]) {
;   float tm = -1e30f;
; #pragma unroll
;   for (int mt = 0; mt < 4; ++mt)
; #pragma unroll
;     for (int j = 0; j < 4; ++j) { float s = st[mt][j] * 0.125f; st[mt][j] = s; if (msk[mt][j]) tm = fmaxf(tm, s); }
;   tm = quad_max(tm);
;   float mn = fmaxf(m, tm);
;   float alpha = __expf(m - mn);
;   float ps = 0.f;
; #pragma unroll
;   for (int mt = 0; mt < 4; ++mt)
; #pragma unroll
;     for (int j = 0; j < 4; ++j) { float p = msk[mt][j] ? __expf(st[mt][j] - mn) : 0.f; st[mt][j] = p; ps += p; }
;   l = l * alpha + ps;
;   m = mn;
; #pragma unroll
;   for (int dt = 0; dt < 4; ++dt)
; #pragma unroll
;     for (int j = 0; j < 4; ++j) ot[dt][j] *= alpha;
; }
; DI void sel_attn_item(const Params& P, int it, u16* sQ, u16* sKunused, u16* sVunused) {
;     ...
;       else {
;         bool msk[4][4];
; #pragma unroll
;         for (int mt = 0; mt < 4; ++mt)
; #pragma unroll
;           for (int j = 0; j < 4; ++j) { int s = kb * 64 + 16 * mt + 4 * quad + j; msk[mt][j] = selq && (s <= tq[qt]); }
;         softmax_tile(st, msk, m[qt], lsum[qt], ot[qt]);
.LBB0_248:
	v_or_b32_e32 v226, v222, v209
	v_or_b32_e32 v232, 2, v226
	v_or_b32_e32 v231, 3, v226
	v_or_b32_e32 v230, 16, v226
	v_or_b32_e32 v229, 17, v226
	v_or_b32_e32 v228, 18, v226
	v_or_b32_e32 v227, 19, v226
	v_or_b32_e32 v225, 32, v226
	v_or_b32_e32 v224, 33, v226
	v_or_b32_e32 v223, 34, v226
	v_or_b32_e32 v222, 35, v226
	s_andn2_b64 vcc, exec, s[2:3]
	v_cmp_le_i32_e64 s[8:9], v226, v172
	v_cmp_lt_i32_e64 s[14:15], v226, v172
	v_cmp_le_i32_e64 s[20:21], v232, v172
	v_cmp_le_i32_e64 s[26:27], v231, v172
	v_cmp_le_i32_e64 s[24:25], v230, v172
	v_cmp_le_i32_e64 s[10:11], v229, v172
	v_cmp_le_i32_e64 s[18:19], v228, v172
	v_cmp_le_i32_e64 s[22:23], v227, v172
	v_cmp_le_i32_e64 s[4:5], v225, v172
	v_cmp_le_i32_e64 s[12:13], v224, v172
	v_cmp_le_i32_e64 s[16:17], v223, v172
	v_cmp_le_i32_e64 s[6:7], v222, v172
	s_cbranch_vccnz .LBB0_250
	v_or_b32_e32 v0, 48, v226
	v_cmp_le_i32_e64 s[2:3], v0, v172
	v_or_b32_e32 v0, 49, v226
	v_cmp_le_i32_e64 s[30:31], v0, v172
	v_or_b32_e32 v0, 50, v226
	v_cmp_le_i32_e64 s[34:35], v0, v172
	v_or_b32_e32 v0, 51, v226
	v_cmp_le_i32_e64 s[36:37], v0, v172
	v_mul_f32_e32 v0, 0x3e000000, v156
	v_max_f32_e32 v0, 0xf149f2ca, v0
	s_and_b64 s[8:9], s[0:1], s[8:9]
	v_cndmask_b32_e64 v0, v186, v0, s[8:9]
	v_mul_f32_e32 v1, 0x3e000000, v157
	v_max_f32_e32 v1, v0, v1
	s_and_b64 s[14:15], s[0:1], s[14:15]
	v_cndmask_b32_e64 v0, v0, v1, s[14:15]
	v_mul_f32_e32 v1, 0x3e000000, v158
	v_max_f32_e32 v1, v0, v1
	s_and_b64 s[20:21], s[0:1], s[20:21]
	v_cndmask_b32_e64 v0, v0, v1, s[20:21]
	v_mul_f32_e32 v1, 0x3e000000, v159
	v_max_f32_e32 v1, v0, v1
	s_and_b64 s[26:27], s[0:1], s[26:27]
	v_cndmask_b32_e64 v0, v0, v1, s[26:27]
	v_mul_f32_e32 v1, 0x3e000000, v152
	v_max_f32_e32 v1, v0, v1
	s_and_b64 vcc, s[0:1], s[24:25]
	v_cndmask_b32_e32 v0, v0, v1, vcc
	v_mul_f32_e32 v1, 0x3e000000, v153
	v_max_f32_e32 v2, v0, v0
	v_max_f32_e32 v1, v2, v1
	s_and_b64 s[10:11], s[0:1], s[10:11]
	v_cndmask_b32_e64 v0, v0, v1, s[10:11]
	v_mul_f32_e32 v1, 0x3e000000, v154
	v_max_f32_e32 v2, v0, v0
	v_max_f32_e32 v1, v2, v1
	s_and_b64 s[18:19], s[0:1], s[18:19]
	v_cndmask_b32_e64 v0, v0, v1, s[18:19]
	v_mul_f32_e32 v1, 0x3e000000, v155
	v_max_f32_e32 v2, v0, v0
	v_max_f32_e32 v1, v2, v1
	s_and_b64 s[24:25], s[0:1], s[22:23]
	v_cndmask_b32_e64 v0, v0, v1, s[24:25]
	v_mul_f32_e32 v1, 0x3e000000, v148
	v_max_f32_e32 v2, v0, v0
	v_max_f32_e32 v1, v2, v1
	s_and_b64 s[4:5], s[0:1], s[4:5]
	v_cndmask_b32_e64 v0, v0, v1, s[4:5]
	v_mul_f32_e32 v1, 0x3e000000, v149
	v_max_f32_e32 v2, v0, v0
	v_max_f32_e32 v1, v2, v1
	s_and_b64 s[12:13], s[0:1], s[12:13]
	v_cndmask_b32_e64 v0, v0, v1, s[12:13]
	v_mul_f32_e32 v1, 0x3e000000, v150
	v_max_f32_e32 v2, v0, v0
	v_max_f32_e32 v1, v2, v1
	s_and_b64 s[22:23], s[0:1], s[16:17]
	v_cndmask_b32_e64 v0, v0, v1, s[22:23]
	v_mul_f32_e32 v1, 0x3e000000, v151
	v_max_f32_e32 v2, v0, v0
	v_max_f32_e32 v1, v2, v1
	s_and_b64 s[38:39], s[0:1], s[6:7]
	v_cndmask_b32_e64 v0, v0, v1, s[38:39]
	v_mul_f32_e32 v1, 0x3e000000, v144
	v_max_f32_e32 v2, v0, v0
	v_max_f32_e32 v1, v2, v1
	s_and_b64 s[6:7], s[0:1], s[2:3]
	v_cndmask_b32_e64 v0, v0, v1, s[6:7]
	v_mul_f32_e32 v1, 0x3e000000, v145
	v_max_f32_e32 v2, v0, v0
	v_max_f32_e32 v1, v2, v1
	s_and_b64 s[16:17], s[0:1], s[30:31]
	v_cndmask_b32_e64 v0, v0, v1, s[16:17]
	v_mul_f32_e32 v1, 0x3e000000, v146
	v_max_f32_e32 v2, v0, v0
	v_max_f32_e32 v1, v2, v1
	s_and_b64 s[2:3], s[0:1], s[34:35]
	v_cndmask_b32_e64 v0, v0, v1, s[2:3]
	v_mul_f32_e32 v1, 0x3e000000, v147
	v_max_f32_e32 v2, v0, v0
	v_max_f32_e32 v1, v2, v1
	s_and_b64 s[0:1], s[0:1], s[36:37]
	v_cndmask_b32_e64 v0, v0, v1, s[0:1]
	v_mbcnt_hi_u32_b32 v1, -1, v184
	v_and_b32_e32 v3, 64, v1
	v_xor_b32_e32 v2, 16, v1
	v_add_u32_e32 v3, 64, v3
	v_cmp_lt_i32_e64 s[30:31], v2, v3
	s_nop 1
	v_cndmask_b32_e64 v2, v1, v2, s[30:31]
	v_lshlrev_b32_e32 v2, 2, v2
	v_mov_b32_e32 v2, v0
	v_mov_b32_e32 v254, v0
	s_nop 1
	v_permlane16_swap_b32_e32 v2, v254
	s_nop 0
	v_max_f32_e32 v2, v2, v254
	v_max_f32_e32 v0, v0, v0
	s_waitcnt lgkmcnt(0)
	v_max_f32_e32 v2, v2, v2
	v_max_f32_e32 v0, v0, v2
	v_xor_b32_e32 v2, 32, v1
	v_cmp_lt_i32_e64 s[30:31], v2, v3
	s_nop 1
	v_cndmask_b32_e64 v1, v1, v2, s[30:31]
	v_lshlrev_b32_e32 v1, 2, v1
	v_mov_b32_e32 v1, v0
	v_mov_b32_e32 v254, v0
	s_nop 1
	v_permlane32_swap_b32_e32 v1, v254
	s_nop 0
	v_max_f32_e32 v1, v1, v254
	s_waitcnt lgkmcnt(0)
	v_max3_f32 v220, v221, v0, v1
	v_fma_f32 v0, v156, s33, -v220
	v_mul_f32_e32 v0, 0x3fb8aa3b, v0
	v_fma_f32 v1, v157, s33, -v220
	v_exp_f32_e32 v0, v0
	v_mul_f32_e32 v1, 0x3fb8aa3b, v1
	v_fma_f32 v2, v158, s33, -v220
	v_exp_f32_e32 v1, v1
	v_mul_f32_e32 v2, 0x3fb8aa3b, v2
	v_fma_f32 v3, v159, s33, -v220
	v_exp_f32_e32 v2, v2
	v_mul_f32_e32 v3, 0x3fb8aa3b, v3
	v_fma_f32 v4, v152, s33, -v220
	v_exp_f32_e32 v3, v3
	v_mul_f32_e32 v4, 0x3fb8aa3b, v4
	v_fma_f32 v5, v153, s33, -v220
	v_cndmask_b32_e64 v0, 0, v0, s[8:9]
	v_exp_f32_e32 v4, v4
	v_mul_f32_e32 v5, 0x3fb8aa3b, v5
	v_fma_f32 v6, v154, s33, -v220
	v_cndmask_b32_e64 v1, 0, v1, s[14:15]
	v_exp_f32_e32 v5, v5
	v_mul_f32_e32 v6, 0x3fb8aa3b, v6
	v_fma_f32 v7, v155, s33, -v220
	v_fma_f32 v12, v144, s33, -v220
	v_add_f32_e32 v144, 0, v0
	v_cndmask_b32_e64 v2, 0, v2, s[20:21]
	v_exp_f32_e32 v6, v6
	v_mul_f32_e32 v7, 0x3fb8aa3b, v7
	v_fma_f32 v8, v148, s33, -v220
	v_add_f32_e32 v144, v1, v144
	v_cndmask_b32_e64 v3, 0, v3, s[26:27]
	v_exp_f32_e32 v7, v7
	v_mul_f32_e32 v8, 0x3fb8aa3b, v8
	v_fma_f32 v9, v149, s33, -v220
	v_add_f32_e32 v144, v2, v144
	v_cndmask_b32_e32 v4, 0, v4, vcc
	v_exp_f32_e32 v8, v8
	v_mul_f32_e32 v9, 0x3fb8aa3b, v9
	v_fma_f32 v10, v150, s33, -v220
	v_add_f32_e32 v144, v3, v144
	v_cndmask_b32_e64 v5, 0, v5, s[10:11]
	v_exp_f32_e32 v9, v9
	v_mul_f32_e32 v10, 0x3fb8aa3b, v10
	v_fma_f32 v11, v151, s33, -v220
	v_add_f32_e32 v144, v4, v144
	v_cndmask_b32_e64 v6, 0, v6, s[18:19]
	v_exp_f32_e32 v10, v10
	v_mul_f32_e32 v11, 0x3fb8aa3b, v11
	v_add_f32_e32 v144, v5, v144
	v_cndmask_b32_e64 v7, 0, v7, s[24:25]
	v_exp_f32_e32 v11, v11
	v_mul_f32_e32 v12, 0x3fb8aa3b, v12
	v_fma_f32 v13, v145, s33, -v220
	v_add_f32_e32 v144, v6, v144
	v_cndmask_b32_e64 v8, 0, v8, s[4:5]
	v_exp_f32_e32 v12, v12
	v_mul_f32_e32 v13, 0x3fb8aa3b, v13
	v_fma_f32 v14, v146, s33, -v220
	v_add_f32_e32 v144, v7, v144
	v_cndmask_b32_e64 v9, 0, v9, s[12:13]
	v_exp_f32_e32 v13, v13
	v_mul_f32_e32 v14, 0x3fb8aa3b, v14
	v_fma_f32 v15, v147, s33, -v220
	v_add_f32_e32 v144, v8, v144
	v_cndmask_b32_e64 v10, 0, v10, s[22:23]
	v_exp_f32_e32 v14, v14
	v_mul_f32_e32 v15, 0x3fb8aa3b, v15
	v_add_f32_e32 v144, v9, v144
	v_cndmask_b32_e64 v11, 0, v11, s[38:39]
	v_exp_f32_e32 v15, v15
	v_add_f32_e32 v144, v10, v144
	v_cndmask_b32_e64 v12, 0, v12, s[6:7]
	v_add_f32_e32 v144, v11, v144
	v_cndmask_b32_e64 v13, 0, v13, s[16:17]
	v_add_f32_e32 v144, v12, v144
	v_cndmask_b32_e64 v14, 0, v14, s[2:3]
	v_add_f32_e32 v144, v13, v144
	v_cndmask_b32_e64 v15, 0, v15, s[0:1]
	v_add_f32_e32 v144, v14, v144
	v_add_f32_e32 v162, v15, v144
; DI float quad_max(float v) { v = fmaxf(v, __shfl_xor(v, 16)); v = fmaxf(v, __shfl_xor(v, 32)); return v; }
; DI void softmax_tile_full(f32x4 (&st)[4], float& m, float& l, f32x4 (&ot)[4]) {
;   float tm = st[0][0];
; #pragma unroll
;   for (int mt = 0; mt < 4; ++mt)
; #pragma unroll
;     for (int j = 0; j < 4; ++j) tm = fmaxf(tm, st[mt][j]);
;   tm = quad_max(tm) * 0.125f;
;   const float mn = fmaxf(m, tm);
;   const float alpha = __expf(m - mn);
;   float ps = 0.f;
; #pragma unroll
;   for (int mt = 0; mt < 4; ++mt)
; #pragma unroll
;     for (int j = 0; j < 4; ++j) { const float p = __expf(st[mt][j] * 0.125f - mn); st[mt][j] = p; ps += p; }
;   l = l * alpha + ps;
;   m = mn;
; #pragma unroll
;   for (int dt = 0; dt < 4; ++dt)
; #pragma unroll
;     for (int j = 0; j < 4; ++j) ot[dt][j] *= alpha;
; }
; DI void sel_attn_item(const Params& P, int it, u16* sQ, u16* sKunused, u16* sVunused) {
;     ...
; #pragma unroll
;     for (int qt = 0; qt < 2; ++qt) {
;       f32x4 st[4];
;       st_mma(st, sK, bq[qt], lane);
;       const bool selq = (mysel[qt] >> kb) & 1ull;
;       if (__ballot(selq) == ~0ull && kb * 64 + 63 <= t0 + 16 * qt) softmax_tile_full(st, m[qt], lsum[qt], ot[qt]);
;       else {
;         bool msk[4][4];
; #pragma unroll
;         for (int mt = 0; mt < 4; ++mt)
; #pragma unroll
;           for (int j = 0; j < 4; ++j) { int s = kb * 64 + 16 * mt + 4 * quad + j; msk[mt][j] = selq && (s <= tq[qt]); }
;         softmax_tile(st, msk, m[qt], lsum[qt], ot[qt]);
;       }
;       pv_mma(ot[qt], sVt, st, lane);
.LBB0_250:
	v_sub_f32_e32 v144, v221, v220
	v_mul_f32_e32 v144, 0x3fb8aa3b, v144
	v_exp_f32_e32 v144, v144
	v_cvt_pk_bf16_f32 v0, v0, v1
	v_cvt_pk_bf16_f32 v1, v2, v3
	v_cvt_pk_bf16_f32 v2, v4, v5
	v_pk_mul_f32 v[46:47], v[46:47], v[144:145] op_sel_hi:[1,0]
	v_pk_mul_f32 v[44:45], v[44:45], v[144:145] op_sel_hi:[1,0]
	v_cvt_pk_bf16_f32 v3, v6, v7
	v_pk_mul_f32 v[42:43], v[42:43], v[144:145] op_sel_hi:[1,0]
	v_pk_mul_f32 v[40:41], v[40:41], v[144:145] op_sel_hi:[1,0]
	v_pk_mul_f32 v[38:39], v[38:39], v[144:145] op_sel_hi:[1,0]
	v_pk_mul_f32 v[36:37], v[36:37], v[144:145] op_sel_hi:[1,0]
	v_pk_mul_f32 v[34:35], v[34:35], v[144:145] op_sel_hi:[1,0]
	v_pk_mul_f32 v[32:33], v[32:33], v[144:145] op_sel_hi:[1,0]
	v_mfma_f32_16x16x32_bf16 v[4:7], v[108:111], v[0:3], v[44:47]
	v_cvt_pk_bf16_f32 v8, v8, v9
	v_cvt_pk_bf16_f32 v9, v10, v11
	v_cvt_pk_bf16_f32 v10, v12, v13
	v_mfma_f32_16x16x32_bf16 v[40:43], v[104:107], v[0:3], v[40:43]
	v_cvt_pk_bf16_f32 v11, v14, v15
	v_cmp_gt_i32_e32 vcc, v233, v213
	v_mfma_f32_16x16x32_bf16 v[36:39], v[100:103], v[0:3], v[36:39]
	v_mfma_f32_16x16x32_bf16 v[0:3], v[96:99], v[0:3], v[32:35]
	v_mfma_f32_16x16x32_bf16 v[32:35], v[80:83], v[8:11], v[0:3]
	v_mfma_f32_16x16x32_bf16 v[0:3], v[124:127], v[56:59], 0
	v_mfma_f32_16x16x32_bf16 v[128:131], v[128:131], v[60:63], v[0:3]
	v_mfma_f32_16x16x32_bf16 v[0:3], v[132:135], v[56:59], 0
	v_mfma_f32_16x16x32_bf16 v[124:127], v[136:139], v[60:63], v[0:3]
	v_mfma_f32_16x16x32_bf16 v[0:3], v[140:143], v[56:59], 0
	v_mfma_f32_16x16x32_bf16 v[132:135], v[116:119], v[56:59], 0
	v_mfma_f32_16x16x32_bf16 v[44:47], v[92:95], v[8:11], v[4:7]
	s_nop 2
	v_and_b32_e32 v5, v181, v177
	v_and_b32_e32 v4, v180, v176
	v_cmp_ne_u64_e64 s[0:1], 0, v[4:5]
	v_mfma_f32_16x16x32_bf16 v[40:43], v[88:91], v[8:11], v[40:43]
	s_cmp_lg_u64 s[0:1], -1
	s_cselect_b64 s[2:3], -1, 0
	s_or_b64 s[4:5], s[2:3], vcc
	s_waitcnt lgkmcnt(0)
	v_mfma_f32_16x16x32_bf16 v[36:39], v[84:87], v[8:11], v[36:39]
	s_mov_b64 s[2:3], -1
	s_and_b64 vcc, exec, s[4:5]
	v_mfma_f32_16x16x32_bf16 v[120:123], v[120:123], v[60:63], v[0:3]
	v_mfma_f32_16x16x32_bf16 v[112:115], v[112:115], v[60:63], v[132:135]
	s_cbranch_vccnz .LBB0_252
	s_nop 0
	v_max_f32_e32 v0, v129, v129
	v_max_f32_e32 v1, v128, v128
	v_max_f32_e32 v0, v1, v0
	v_max3_f32 v0, v0, v130, v131
	v_max3_f32 v0, v0, v124, v125
	v_mbcnt_hi_u32_b32 v1, -1, v184
	v_max3_f32 v0, v0, v126, v127
	v_and_b32_e32 v3, 64, v1
	v_max3_f32 v0, v0, v120, v121
	v_xor_b32_e32 v2, 16, v1
	v_add_u32_e32 v3, 64, v3
	v_max3_f32 v0, v0, v122, v123
	v_cmp_lt_i32_e32 vcc, v2, v3
	v_max3_f32 v0, v0, v112, v113
	v_max3_f32 v0, v0, v114, v115
	v_cndmask_b32_e32 v2, v1, v2, vcc
	v_lshlrev_b32_e32 v2, 2, v2
	v_mov_b32_e32 v2, v0
	v_mov_b32_e32 v254, v0
	s_nop 1
	v_permlane16_swap_b32_e32 v2, v254
	s_nop 0
	v_max_f32_e32 v2, v2, v254
	s_mov_b64 s[2:3], 0
	s_waitcnt lgkmcnt(0)
	v_max_f32_e32 v2, v2, v2
	v_max_f32_e32 v0, v0, v2
	v_xor_b32_e32 v2, 32, v1
	v_cmp_lt_i32_e32 vcc, v2, v3
	s_nop 1
	v_cndmask_b32_e32 v1, v1, v2, vcc
	v_lshlrev_b32_e32 v1, 2, v1
	v_mov_b32_e32 v1, v0
	v_mov_b32_e32 v254, v0
	s_nop 1
	v_permlane32_swap_b32_e32 v1, v254
	s_nop 0
	v_max_f32_e32 v1, v1, v254
	s_waitcnt lgkmcnt(0)
	v_max_f32_e32 v1, v1, v1
	v_max_f32_e32 v0, v0, v1
	v_mul_f32_e32 v0, 0x3e000000, v0
	v_max_f32_e32 v1, v218, v218
	v_max_f32_e32 v117, v1, v0
	v_fma_f32 v0, v128, s33, -v117
	v_mul_f32_e32 v0, 0x3fb8aa3b, v0
	v_fma_f32 v1, v129, s33, -v117
	v_exp_f32_e32 v0, v0
	v_mul_f32_e32 v1, 0x3fb8aa3b, v1
	v_fma_f32 v2, v130, s33, -v117
	v_exp_f32_e32 v1, v1
	v_mul_f32_e32 v2, 0x3fb8aa3b, v2
	v_fma_f32 v3, v131, s33, -v117
	v_exp_f32_e32 v2, v2
	v_mul_f32_e32 v3, 0x3fb8aa3b, v3
	v_exp_f32_e32 v3, v3
	v_add_f32_e32 v4, 0, v0
	v_add_f32_e32 v4, v1, v4
	v_add_f32_e32 v4, v2, v4
	v_add_f32_e32 v8, v3, v4
	v_fma_f32 v4, v124, s33, -v117
	v_mul_f32_e32 v4, 0x3fb8aa3b, v4
	v_fma_f32 v5, v125, s33, -v117
	v_exp_f32_e32 v4, v4
	v_mul_f32_e32 v5, 0x3fb8aa3b, v5
	v_fma_f32 v6, v126, s33, -v117
	v_exp_f32_e32 v5, v5
	v_mul_f32_e32 v6, 0x3fb8aa3b, v6
	v_fma_f32 v7, v127, s33, -v117
	v_exp_f32_e32 v6, v6
	v_mul_f32_e32 v7, 0x3fb8aa3b, v7
	v_exp_f32_e32 v7, v7
	v_add_f32_e32 v8, v4, v8
	v_add_f32_e32 v8, v5, v8
	v_add_f32_e32 v8, v6, v8
	v_add_f32_e32 v12, v7, v8
	v_fma_f32 v8, v120, s33, -v117
	v_mul_f32_e32 v8, 0x3fb8aa3b, v8
	v_fma_f32 v9, v121, s33, -v117
	v_exp_f32_e32 v8, v8
	v_mul_f32_e32 v9, 0x3fb8aa3b, v9
	v_fma_f32 v10, v122, s33, -v117
	v_exp_f32_e32 v9, v9
	v_mul_f32_e32 v10, 0x3fb8aa3b, v10
	v_fma_f32 v11, v123, s33, -v117
	v_exp_f32_e32 v10, v10
	v_mul_f32_e32 v11, 0x3fb8aa3b, v11
	v_exp_f32_e32 v11, v11
	v_add_f32_e32 v12, v8, v12
	v_add_f32_e32 v12, v9, v12
	v_add_f32_e32 v12, v10, v12
	v_add_f32_e32 v116, v11, v12
	v_fma_f32 v12, v112, s33, -v117
	v_mul_f32_e32 v12, 0x3fb8aa3b, v12
	v_fma_f32 v13, v113, s33, -v117
	v_exp_f32_e32 v12, v12
	v_mul_f32_e32 v13, 0x3fb8aa3b, v13
	v_fma_f32 v14, v114, s33, -v117
	v_exp_f32_e32 v13, v13
	v_mul_f32_e32 v14, 0x3fb8aa3b, v14
	v_fma_f32 v15, v115, s33, -v117
	v_exp_f32_e32 v14, v14
	v_mul_f32_e32 v15, 0x3fb8aa3b, v15
	v_exp_f32_e32 v15, v15
	v_add_f32_e32 v116, v12, v116
	v_add_f32_e32 v116, v13, v116
	v_add_f32_e32 v116, v14, v116
	v_add_f32_e32 v116, v15, v116
; DI float quad_max(float v) { v = fmaxf(v, __shfl_xor(v, 16)); v = fmaxf(v, __shfl_xor(v, 32)); return v; }
; DI void softmax_tile(f32x4 (&st)[4], const bool (&msk)[4][4], float& m, float& l, f32x4 (&ot)[4]) {
;   float tm = -1e30f;
; #pragma unroll
;   for (int mt = 0; mt < 4; ++mt)
; #pragma unroll
;     for (int j = 0; j < 4; ++j) { float s = st[mt][j] * 0.125f; st[mt][j] = s; if (msk[mt][j]) tm = fmaxf(tm, s); }
;   tm = quad_max(tm);
;   float mn = fmaxf(m, tm);
;   float alpha = __expf(m - mn);
;   float ps = 0.f;
; #pragma unroll
;   for (int mt = 0; mt < 4; ++mt)
; #pragma unroll
;     for (int j = 0; j < 4; ++j) { float p = msk[mt][j] ? __expf(st[mt][j] - mn) : 0.f; st[mt][j] = p; ps += p; }
;   l = l * alpha + ps;
;   m = mn;
; #pragma unroll
;   for (int dt = 0; dt < 4; ++dt)
; #pragma unroll
;     for (int j = 0; j < 4; ++j) ot[dt][j] *= alpha;
; }
; DI void sel_attn_item(const Params& P, int it, u16* sQ, u16* sKunused, u16* sVunused) {
;     ...
;       else {
;         bool msk[4][4];
; #pragma unroll
;         for (int mt = 0; mt < 4; ++mt)
; #pragma unroll
;           for (int j = 0; j < 4; ++j) { int s = kb * 64 + 16 * mt + 4 * quad + j; msk[mt][j] = selq && (s <= tq[qt]); }
;         softmax_tile(st, msk, m[qt], lsum[qt], ot[qt]);
.LBB0_252:
	s_andn2_b64 vcc, exec, s[2:3]
	s_cbranch_vccnz .LBB0_254
	v_cmp_le_i32_e32 vcc, v226, v168
	v_mul_f32_e32 v0, 0x3e000000, v128
	v_max_f32_e32 v0, 0xf149f2ca, v0
	s_and_b64 s[8:9], s[0:1], vcc
	v_cmp_lt_i32_e64 s[2:3], v226, v168
	v_cndmask_b32_e64 v0, v186, v0, s[8:9]
	v_mul_f32_e32 v1, 0x3e000000, v129
	v_max_f32_e32 v1, v0, v1
	s_and_b64 s[14:15], s[0:1], s[2:3]
	v_cmp_le_i32_e64 s[4:5], v226, v214
	v_cndmask_b32_e64 v0, v0, v1, s[14:15]
	v_mul_f32_e32 v1, 0x3e000000, v130
	v_max_f32_e32 v1, v0, v1
	s_and_b64 s[20:21], s[0:1], s[4:5]
	v_cmp_le_i32_e64 s[6:7], v226, v215
	v_cndmask_b32_e64 v0, v0, v1, s[20:21]
	v_mul_f32_e32 v1, 0x3e000000, v131
	v_max_f32_e32 v1, v0, v1
	s_and_b64 s[2:3], s[0:1], s[6:7]
	v_cmp_le_i32_e64 s[10:11], v226, v172
	v_cndmask_b32_e64 v0, v0, v1, s[2:3]
	v_mul_f32_e32 v1, 0x3e000000, v124
	v_max_f32_e32 v1, v0, v1
	s_and_b64 vcc, s[0:1], s[10:11]
	v_cndmask_b32_e32 v0, v0, v1, vcc
	v_cmp_lt_i32_e64 s[12:13], v226, v172
	v_mul_f32_e32 v1, 0x3e000000, v125
	v_max_f32_e32 v2, v0, v0
	v_max_f32_e32 v1, v2, v1
	s_and_b64 s[10:11], s[0:1], s[12:13]
	v_cndmask_b32_e64 v0, v0, v1, s[10:11]
	v_cmp_le_i32_e64 s[16:17], v232, v172
	v_mul_f32_e32 v1, 0x3e000000, v126
	v_max_f32_e32 v2, v0, v0
	v_max_f32_e32 v1, v2, v1
	s_and_b64 s[18:19], s[0:1], s[16:17]
	v_cndmask_b32_e64 v0, v0, v1, s[18:19]
	v_cmp_le_i32_e64 s[22:23], v231, v172
	v_mul_f32_e32 v1, 0x3e000000, v127
	v_max_f32_e32 v2, v0, v0
	v_max_f32_e32 v1, v2, v1
	s_and_b64 s[44:45], s[0:1], s[22:23]
	v_cndmask_b32_e64 v0, v0, v1, s[44:45]
	v_cmp_le_i32_e64 s[24:25], v230, v172
	v_mul_f32_e32 v1, 0x3e000000, v120
	v_max_f32_e32 v2, v0, v0
	v_max_f32_e32 v1, v2, v1
	s_and_b64 s[4:5], s[0:1], s[24:25]
	v_cndmask_b32_e64 v0, v0, v1, s[4:5]
	v_cmp_le_i32_e64 s[26:27], v229, v172
	v_mul_f32_e32 v1, 0x3e000000, v121
	v_max_f32_e32 v2, v0, v0
	v_max_f32_e32 v1, v2, v1
	s_and_b64 s[12:13], s[0:1], s[26:27]
	v_cndmask_b32_e64 v0, v0, v1, s[12:13]
	v_cmp_le_i32_e64 s[30:31], v228, v172
	v_mul_f32_e32 v1, 0x3e000000, v122
	v_max_f32_e32 v2, v0, v0
	v_max_f32_e32 v1, v2, v1
	s_and_b64 s[22:23], s[0:1], s[30:31]
	v_cndmask_b32_e64 v0, v0, v1, s[22:23]
	v_cmp_le_i32_e64 s[34:35], v227, v172
	v_mul_f32_e32 v1, 0x3e000000, v123
	v_max_f32_e32 v2, v0, v0
	v_max_f32_e32 v1, v2, v1
	s_and_b64 s[24:25], s[0:1], s[34:35]
	v_cndmask_b32_e64 v0, v0, v1, s[24:25]
	v_cmp_le_i32_e64 s[36:37], v225, v172
	v_mul_f32_e32 v1, 0x3e000000, v112
	v_max_f32_e32 v2, v0, v0
	v_max_f32_e32 v1, v2, v1
	s_and_b64 s[6:7], s[0:1], s[36:37]
	v_cndmask_b32_e64 v0, v0, v1, s[6:7]
	v_cmp_le_i32_e64 s[38:39], v224, v172
	v_mul_f32_e32 v1, 0x3e000000, v113
	v_max_f32_e32 v2, v0, v0
	v_max_f32_e32 v1, v2, v1
	s_and_b64 s[16:17], s[0:1], s[38:39]
	v_cndmask_b32_e64 v0, v0, v1, s[16:17]
	v_cmp_le_i32_e64 s[40:41], v223, v172
	v_mul_f32_e32 v1, 0x3e000000, v114
	v_max_f32_e32 v2, v0, v0
	v_max_f32_e32 v1, v2, v1
	s_and_b64 s[26:27], s[0:1], s[40:41]
	v_cndmask_b32_e64 v0, v0, v1, s[26:27]
	v_cmp_le_i32_e64 s[42:43], v222, v172
	v_mul_f32_e32 v1, 0x3e000000, v115
	v_max_f32_e32 v2, v0, v0
	v_max_f32_e32 v1, v2, v1
	s_and_b64 s[0:1], s[0:1], s[42:43]
	v_cndmask_b32_e64 v0, v0, v1, s[0:1]
	v_mbcnt_hi_u32_b32 v1, -1, v184
	v_and_b32_e32 v3, 64, v1
	v_xor_b32_e32 v2, 16, v1
	v_add_u32_e32 v3, 64, v3
	v_cmp_lt_i32_e64 s[30:31], v2, v3
	v_readlane_b32 s40, v246, 45
	v_readlane_b32 s41, v246, 46
	v_cndmask_b32_e64 v2, v1, v2, s[30:31]
	v_lshlrev_b32_e32 v2, 2, v2
	v_mov_b32_e32 v2, v0
	v_mov_b32_e32 v254, v0
	s_nop 1
	v_permlane16_swap_b32_e32 v2, v254
	s_nop 0
	v_max_f32_e32 v2, v2, v254
	v_max_f32_e32 v0, v0, v0
	s_waitcnt lgkmcnt(0)
	v_max_f32_e32 v2, v2, v2
	v_max_f32_e32 v0, v0, v2
	v_xor_b32_e32 v2, 32, v1
	v_cmp_lt_i32_e64 s[30:31], v2, v3
	s_nop 1
	v_cndmask_b32_e64 v1, v1, v2, s[30:31]
	v_lshlrev_b32_e32 v1, 2, v1
	v_mov_b32_e32 v1, v0
	v_mov_b32_e32 v254, v0
	s_nop 1
	v_permlane32_swap_b32_e32 v1, v254
	s_nop 0
	v_max_f32_e32 v1, v1, v254
	s_waitcnt lgkmcnt(0)
	v_max3_f32 v117, v218, v0, v1
	v_fma_f32 v0, v128, s33, -v117
	v_mul_f32_e32 v0, 0x3fb8aa3b, v0
	v_fma_f32 v1, v129, s33, -v117
	v_exp_f32_e32 v0, v0
	v_mul_f32_e32 v1, 0x3fb8aa3b, v1
	v_fma_f32 v2, v130, s33, -v117
	v_exp_f32_e32 v1, v1
	v_mul_f32_e32 v2, 0x3fb8aa3b, v2
	v_fma_f32 v3, v131, s33, -v117
	v_exp_f32_e32 v2, v2
	v_mul_f32_e32 v3, 0x3fb8aa3b, v3
	v_fma_f32 v4, v124, s33, -v117
	v_exp_f32_e32 v3, v3
	v_mul_f32_e32 v4, 0x3fb8aa3b, v4
	v_fma_f32 v5, v125, s33, -v117
	v_cndmask_b32_e64 v0, 0, v0, s[8:9]
	v_exp_f32_e32 v4, v4
	v_mul_f32_e32 v5, 0x3fb8aa3b, v5
	v_fma_f32 v6, v126, s33, -v117
	v_cndmask_b32_e64 v1, 0, v1, s[14:15]
	v_exp_f32_e32 v5, v5
	v_mul_f32_e32 v6, 0x3fb8aa3b, v6
	v_fma_f32 v7, v127, s33, -v117
	v_fma_f32 v12, v112, s33, -v117
	v_add_f32_e32 v112, 0, v0
	v_cndmask_b32_e64 v2, 0, v2, s[20:21]
	v_exp_f32_e32 v6, v6
	v_mul_f32_e32 v7, 0x3fb8aa3b, v7
	v_fma_f32 v8, v120, s33, -v117
	v_add_f32_e32 v112, v1, v112
	v_cndmask_b32_e64 v3, 0, v3, s[2:3]
	v_exp_f32_e32 v7, v7
	v_mul_f32_e32 v8, 0x3fb8aa3b, v8
	v_fma_f32 v9, v121, s33, -v117
	v_add_f32_e32 v112, v2, v112
	v_cndmask_b32_e32 v4, 0, v4, vcc
	v_exp_f32_e32 v8, v8
	v_mul_f32_e32 v9, 0x3fb8aa3b, v9
	v_fma_f32 v10, v122, s33, -v117
	v_add_f32_e32 v112, v3, v112
	v_cndmask_b32_e64 v5, 0, v5, s[10:11]
	v_exp_f32_e32 v9, v9
	v_mul_f32_e32 v10, 0x3fb8aa3b, v10
	v_fma_f32 v11, v123, s33, -v117
	v_add_f32_e32 v112, v4, v112
	v_cndmask_b32_e64 v6, 0, v6, s[18:19]
	v_exp_f32_e32 v10, v10
	v_mul_f32_e32 v11, 0x3fb8aa3b, v11
	v_add_f32_e32 v112, v5, v112
	v_cndmask_b32_e64 v7, 0, v7, s[44:45]
	v_exp_f32_e32 v11, v11
	v_mul_f32_e32 v12, 0x3fb8aa3b, v12
	v_fma_f32 v13, v113, s33, -v117
	v_add_f32_e32 v112, v6, v112
	v_cndmask_b32_e64 v8, 0, v8, s[4:5]
	v_exp_f32_e32 v12, v12
	v_mul_f32_e32 v13, 0x3fb8aa3b, v13
	v_fma_f32 v14, v114, s33, -v117
	v_add_f32_e32 v112, v7, v112
	v_cndmask_b32_e64 v9, 0, v9, s[12:13]
	v_exp_f32_e32 v13, v13
	v_mul_f32_e32 v14, 0x3fb8aa3b, v14
	v_fma_f32 v15, v115, s33, -v117
	v_add_f32_e32 v112, v8, v112
	v_cndmask_b32_e64 v10, 0, v10, s[22:23]
	v_exp_f32_e32 v14, v14
	v_mul_f32_e32 v15, 0x3fb8aa3b, v15
	v_add_f32_e32 v112, v9, v112
	v_cndmask_b32_e64 v11, 0, v11, s[24:25]
	v_exp_f32_e32 v15, v15
	v_add_f32_e32 v112, v10, v112
	v_cndmask_b32_e64 v12, 0, v12, s[6:7]
	v_add_f32_e32 v112, v11, v112
	v_cndmask_b32_e64 v13, 0, v13, s[16:17]
	v_add_f32_e32 v112, v12, v112
	v_cndmask_b32_e64 v14, 0, v14, s[26:27]
	v_add_f32_e32 v112, v13, v112
	v_cndmask_b32_e64 v15, 0, v15, s[0:1]
	v_add_f32_e32 v112, v14, v112
	v_add_f32_e32 v116, v15, v112

; DI float quad_max(float v) { v = fmaxf(v, __shfl_xor(v, 16)); v = fmaxf(v, __shfl_xor(v, 32)); return v; }
; DI void softmax_tile(f32x4 (&st)[4], const bool (&msk)[4][4], float& m, float& l, f32x4 (&ot)[4]) {
;   float tm = -1e30f;
; #pragma unroll
;   for (int mt = 0; mt < 4; ++mt)
; #pragma unroll
;     for (int j = 0; j < 4; ++j) { float s = st[mt][j] * 0.125f; st[mt][j] = s; if (msk[mt][j]) tm = fmaxf(tm, s); }
;   tm = quad_max(tm);
; DI void win_attn_item(const Params& P, int it, u16* sQ, u16* sKunused, u16* sVunused) {
;     ...
; #pragma unroll
;     for (int qt = 0; qt < 2; ++qt) {
;       f32x4 st[4];
;       st_mma(st, sK, bq[qt], lane);
;       const int tqlo = t0 + 16 * qt;
;       if (kb * 64 + 63 <= tqlo && tqlo + 15 - kb * 64 < 512) softmax_tile_full(st, m[qt], lsum[qt], ot[qt]);
;       else {
;         bool msk[4][4];
; #pragma unroll
;         for (int mt = 0; mt < 4; ++mt)
; #pragma unroll
;           for (int j = 0; j < 4; ++j) { int s = kb * 64 + 16 * mt + 4 * quad + j; int df = tq[qt] - s; msk[mt][j] = (df >= 0) && (df < 512); }
.LBB0_447:
	ds_read_b128 v[116:119], v170 offset:18432
	v_add_u32_e32 v10, 0x7000, v172
	ds_read_b128 v[120:123], v170 offset:18496
	ds_read_b128 v[124:127], v170 offset:20736
	ds_read_b128 v[128:131], v170 offset:20800
	ds_read_b128 v[132:135], v170 offset:23040
	ds_read_b128 v[112:115], v170 offset:23104
	ds_read2_b64 v[4:7], v10 offset0:160 offset1:164
	ds_read_b128 v[140:143], v171 offset:18432
	ds_read_b128 v[136:139], v171 offset:18496
	v_add_u32_e32 v13, 0x6800, v173
	s_sub_i32 s50, s49, 63
	s_waitcnt lgkmcnt(2)
	v_mov_b64_e32 v[104:105], v[6:7]
	ds_read2_b64 v[6:9], v13 offset0:136 offset1:140
	v_mov_b64_e32 v[106:107], v[4:5]
	v_mfma_f32_16x16x32_bf16 v[0:3], v[116:119], v[48:51], 0
	v_add_u32_e32 v12, 0x6800, v172
	v_add_u32_e32 v14, 0x7800, v172
	s_waitcnt lgkmcnt(0)
	v_mov_b64_e32 v[98:99], v[6:7]
	v_mfma_f32_16x16x32_bf16 v[156:159], v[120:123], v[52:55], v[0:3]
	v_mov_b64_e32 v[96:97], v[8:9]
	ds_read2_b64 v[8:11], v10 offset0:168 offset1:172
	ds_read2_b64 v[108:111], v12 offset0:128 offset1:132
	v_mfma_f32_16x16x32_bf16 v[0:3], v[124:127], v[48:51], 0
	ds_read2_b64 v[100:103], v14 offset0:200 offset1:204
	ds_read2_b64 v[80:83], v12 offset0:136 offset1:140
	ds_read2_b64 v[88:91], v14 offset0:192 offset1:196
	v_mfma_f32_16x16x32_bf16 v[152:155], v[128:131], v[52:55], v[0:3]
	s_cmp_le_u32 s49, s42
	s_cselect_b64 s[0:1], -1, 0
	s_cmp_gt_i32 s50, s46
	v_mfma_f32_16x16x32_bf16 v[0:3], v[132:135], v[48:51], 0
	s_cselect_b64 s[4:5], -1, 0
	s_and_b64 s[0:1], s[0:1], s[4:5]
	v_add_u32_e32 v217, 17, v174
	v_mfma_f32_16x16x32_bf16 v[4:7], v[140:143], v[48:51], 0
	v_add_u32_e32 v216, 15, v174
	v_add_u32_e32 v215, 14, v174
	v_add_u32_e32 v214, 1, v174
	v_mfma_f32_16x16x32_bf16 v[148:151], v[112:115], v[52:55], v[0:3]
	s_movk_i32 s6, 0x200
	v_add_u32_e32 v213, -1, v174
	v_add_u32_e32 v212, -2, v174
	ds_read2_b64 v[0:3], v13 offset0:128 offset1:132
	v_mfma_f32_16x16x32_bf16 v[144:147], v[136:139], v[52:55], v[4:7]
	v_add_u32_e32 v211, -15, v174
	v_add_u32_e32 v210, -16, v174
	v_subrev_u32_e32 v209, 17, v174
	v_subrev_u32_e32 v181, 18, v174
	s_waitcnt lgkmcnt(5)
	v_mov_b64_e32 v[92:93], v[10:11]
	v_mov_b64_e32 v[94:95], v[8:9]
	s_waitcnt lgkmcnt(0)
	v_mov_b64_e32 v[86:87], v[0:1]
	v_mov_b64_e32 v[84:85], v[2:3]
	s_mov_b64 s[22:23], -1
	s_andn2_b64 vcc, exec, s[0:1]
	v_add_u32_e32 v218, s49, v175
	v_cmp_gt_u32_e64 s[8:9], s6, v174
	v_cmp_gt_u32_e64 s[20:21], s6, v217
	v_cmp_gt_u32_e64 s[16:17], s6, v216
	v_cmp_gt_u32_e64 s[18:19], s6, v215
	v_cmp_gt_u32_e64 s[14:15], s6, v214
	v_cmp_gt_u32_e64 s[10:11], s6, v213
	v_cmp_gt_u32_e64 s[12:13], s6, v212
	v_cmp_gt_u32_e64 s[0:1], s6, v211
	v_cmp_gt_u32_e64 s[24:25], s6, v210
	v_cmp_gt_u32_e64 s[4:5], s6, v209
	v_cmp_gt_u32_e64 s[6:7], s6, v181
	s_cbranch_vccz .LBB0_449
	v_mul_f32_e32 v5, 0x3e000000, v156
	v_max_f32_e32 v5, 0xf149f2ca, v5
	v_subrev_u32_e32 v0, 63, v218
	v_cndmask_b32_e64 v5, v186, v5, s[20:21]
	v_mul_f32_e32 v6, 0x3e000000, v157
	s_movk_i32 s22, 0xfdff
	v_max_f32_e32 v6, v5, v6
	v_cmp_lt_u32_e64 s[26:27], s22, v0
	v_subrev_u32_e32 v1, 31, v174
	s_movk_i32 s30, 0x200
	v_cndmask_b32_e64 v0, v5, v6, s[26:27]
	v_mul_f32_e32 v5, 0x3e000000, v158
	v_max_f32_e32 v5, v0, v5
	v_cndmask_b32_e64 v0, v0, v5, s[16:17]
	v_mul_f32_e32 v5, 0x3e000000, v159
	v_max_f32_e32 v5, v0, v5
	v_cndmask_b32_e64 v0, v0, v5, s[18:19]
	v_mul_f32_e32 v5, 0x3e000000, v152
	v_max_f32_e32 v5, v0, v5
	v_cndmask_b32_e64 v0, v0, v5, s[14:15]
	v_mul_f32_e32 v5, 0x3e000000, v153
	v_max_f32_e32 v6, v0, v0
	v_max_f32_e32 v5, v6, v5
	v_cndmask_b32_e64 v0, v0, v5, s[8:9]
	v_mul_f32_e32 v5, 0x3e000000, v154
	v_max_f32_e32 v6, v0, v0
	v_max_f32_e32 v5, v6, v5
	v_cndmask_b32_e64 v0, v0, v5, s[10:11]
	v_mul_f32_e32 v5, 0x3e000000, v155
	v_max_f32_e32 v6, v0, v0
	v_max_f32_e32 v5, v6, v5
	v_cndmask_b32_e64 v0, v0, v5, s[12:13]
	v_mul_f32_e32 v5, 0x3e000000, v148
	v_max_f32_e32 v6, v0, v0
	v_max_f32_e32 v5, v6, v5
	v_cndmask_b32_e64 v0, v0, v5, s[0:1]
	v_mul_f32_e32 v5, 0x3e000000, v149
	v_max_f32_e32 v6, v0, v0
	v_max_f32_e32 v5, v6, v5
	v_cndmask_b32_e64 v0, v0, v5, s[24:25]
	v_mul_f32_e32 v5, 0x3e000000, v150
	v_max_f32_e32 v6, v0, v0
	v_max_f32_e32 v5, v6, v5
	v_cndmask_b32_e64 v0, v0, v5, s[4:5]
	v_mul_f32_e32 v5, 0x3e000000, v151
	v_max_f32_e32 v6, v0, v0
	v_max_f32_e32 v5, v6, v5
	v_cndmask_b32_e64 v0, v0, v5, s[6:7]
	v_mul_f32_e32 v5, 0x3e000000, v144
	v_max_f32_e32 v6, v0, v0
	v_max_f32_e32 v5, v6, v5
	v_cmp_gt_u32_e32 vcc, s30, v1
	v_subrev_u32_e32 v2, 32, v174
	v_mul_f32_e32 v1, 0x3e000000, v145
	v_cndmask_b32_e32 v0, v0, v5, vcc
	v_max_f32_e32 v5, v0, v0
	v_max_f32_e32 v1, v5, v1
	v_cmp_gt_u32_e64 s[22:23], s30, v2
	v_subrev_u32_e32 v3, 33, v174
	v_cmp_gt_u32_e64 s[28:29], s30, v3
	v_cndmask_b32_e64 v0, v0, v1, s[22:23]
	v_mul_f32_e32 v1, 0x3e000000, v146
	v_max_f32_e32 v2, v0, v0
	v_max_f32_e32 v1, v2, v1
	v_cndmask_b32_e64 v0, v0, v1, s[28:29]
	v_subrev_u32_e32 v4, 34, v174
	v_mul_f32_e32 v1, 0x3e000000, v147
	v_max_f32_e32 v2, v0, v0
	v_max_f32_e32 v1, v2, v1
	v_cmp_gt_u32_e64 s[30:31], s30, v4
	v_and_b32_e32 v2, 64, v185
	v_add_u32_e32 v2, 64, v2
	v_cndmask_b32_e64 v0, v0, v1, s[30:31]
	v_xor_b32_e32 v1, 16, v185
	v_cmp_lt_i32_e64 s[34:35], v1, v2
	s_nop 1
	v_cndmask_b32_e64 v1, v185, v1, s[34:35]
	v_lshlrev_b32_e32 v1, 2, v1
	v_mov_b32_e32 v1, v0
	v_mov_b32_e32 v254, v0
	s_nop 1
	v_permlane16_swap_b32_e32 v1, v254
	s_nop 0
	v_max_f32_e32 v1, v1, v254
	v_max_f32_e32 v0, v0, v0
	s_waitcnt lgkmcnt(0)
	v_max_f32_e32 v1, v1, v1
	v_max_f32_e32 v0, v0, v1
	v_xor_b32_e32 v1, 32, v185
	v_cmp_lt_i32_e64 s[34:35], v1, v2
	s_nop 1
	v_cndmask_b32_e64 v1, v185, v1, s[34:35]
	v_lshlrev_b32_e32 v1, 2, v1
	v_mov_b32_e32 v1, v0
	v_mov_b32_e32 v254, v0
	s_nop 1
	v_permlane32_swap_b32_e32 v1, v254
	s_nop 0
	v_max_f32_e32 v1, v1, v254
	s_waitcnt lgkmcnt(0)
; DI float quad_max(float v) { v = fmaxf(v, __shfl_xor(v, 16)); v = fmaxf(v, __shfl_xor(v, 32)); return v; }
; DI void softmax_tile(f32x4 (&st)[4], const bool (&msk)[4][4], float& m, float& l, f32x4 (&ot)[4]) {
;   float tm = -1e30f;
; #pragma unroll
;   for (int mt = 0; mt < 4; ++mt)
; #pragma unroll
;     for (int j = 0; j < 4; ++j) { float s = st[mt][j] * 0.125f; st[mt][j] = s; if (msk[mt][j]) tm = fmaxf(tm, s); }
;   tm = quad_max(tm);
;   float mn = fmaxf(m, tm);
;   float alpha = __expf(m - mn);
;   float ps = 0.f;
; #pragma unroll
;   for (int mt = 0; mt < 4; ++mt)
; #pragma unroll
;     for (int j = 0; j < 4; ++j) { float p = msk[mt][j] ? __expf(st[mt][j] - mn) : 0.f; st[mt][j] = p; ps += p; }
;   l = l * alpha + ps;
; DI void softmax_tile_full(f32x4 (&st)[4], float& m, float& l, f32x4 (&ot)[4]) {
;   float tm = st[0][0];
; #pragma unroll
;   for (int mt = 0; mt < 4; ++mt)
; #pragma unroll
;     for (int j = 0; j < 4; ++j) tm = fmaxf(tm, st[mt][j]);
;   tm = quad_max(tm) * 0.125f;
;   const float mn = fmaxf(m, tm);
;   const float alpha = __expf(m - mn);
;   float ps = 0.f;
; #pragma unroll
;   for (int mt = 0; mt < 4; ++mt)
; #pragma unroll
;     for (int j = 0; j < 4; ++j) { const float p = __expf(st[mt][j] * 0.125f - mn); st[mt][j] = p; ps += p; }
	v_max3_f32 v179, v180, v0, v1
	v_fma_f32 v0, v156, s33, -v179
	v_mul_f32_e32 v0, 0x3fb8aa3b, v0
	v_fma_f32 v1, v157, s33, -v179
	v_exp_f32_e32 v0, v0
	v_mul_f32_e32 v1, 0x3fb8aa3b, v1
	v_fma_f32 v2, v158, s33, -v179
	v_exp_f32_e32 v1, v1
	v_mul_f32_e32 v2, 0x3fb8aa3b, v2
	v_fma_f32 v3, v159, s33, -v179
	v_exp_f32_e32 v2, v2
	v_mul_f32_e32 v3, 0x3fb8aa3b, v3
	v_fma_f32 v4, v152, s33, -v179
	v_exp_f32_e32 v3, v3
	v_mul_f32_e32 v4, 0x3fb8aa3b, v4
	v_fma_f32 v5, v153, s33, -v179
	v_cndmask_b32_e64 v0, 0, v0, s[20:21]
	v_exp_f32_e32 v4, v4
	v_mul_f32_e32 v5, 0x3fb8aa3b, v5
	v_fma_f32 v6, v154, s33, -v179
	v_cndmask_b32_e64 v1, 0, v1, s[26:27]
	v_exp_f32_e32 v5, v5
	v_mul_f32_e32 v6, 0x3fb8aa3b, v6
	v_fma_f32 v7, v155, s33, -v179
	v_add_f32_e32 v162, 0, v0
	v_cndmask_b32_e64 v2, 0, v2, s[16:17]
	v_exp_f32_e32 v6, v6
	v_mul_f32_e32 v7, 0x3fb8aa3b, v7
	v_fma_f32 v8, v148, s33, -v179
	v_add_f32_e32 v162, v1, v162
	v_cndmask_b32_e64 v3, 0, v3, s[18:19]
	v_exp_f32_e32 v7, v7
	v_mul_f32_e32 v8, 0x3fb8aa3b, v8
	v_fma_f32 v9, v149, s33, -v179
	v_add_f32_e32 v162, v2, v162
	v_cndmask_b32_e64 v4, 0, v4, s[14:15]
	v_exp_f32_e32 v8, v8
	v_mul_f32_e32 v9, 0x3fb8aa3b, v9
	v_fma_f32 v10, v150, s33, -v179
	v_add_f32_e32 v162, v3, v162
	v_cndmask_b32_e64 v5, 0, v5, s[8:9]
	v_exp_f32_e32 v9, v9
	v_mul_f32_e32 v10, 0x3fb8aa3b, v10
	v_fma_f32 v11, v151, s33, -v179
	v_add_f32_e32 v162, v4, v162
	v_cndmask_b32_e64 v6, 0, v6, s[10:11]
	v_exp_f32_e32 v10, v10
	v_mul_f32_e32 v11, 0x3fb8aa3b, v11
	v_fma_f32 v12, v144, s33, -v179
	v_add_f32_e32 v162, v5, v162
	v_cndmask_b32_e64 v7, 0, v7, s[12:13]
	v_exp_f32_e32 v11, v11
	v_mul_f32_e32 v12, 0x3fb8aa3b, v12
	v_fma_f32 v13, v145, s33, -v179
	v_add_f32_e32 v162, v6, v162
	v_cndmask_b32_e64 v8, 0, v8, s[0:1]
	v_exp_f32_e32 v12, v12
	v_mul_f32_e32 v13, 0x3fb8aa3b, v13
	v_fma_f32 v14, v146, s33, -v179
	v_add_f32_e32 v162, v7, v162
	v_cndmask_b32_e64 v9, 0, v9, s[24:25]
	v_exp_f32_e32 v13, v13
	v_mul_f32_e32 v14, 0x3fb8aa3b, v14
	v_fma_f32 v15, v147, s33, -v179
	v_add_f32_e32 v162, v8, v162
	v_cndmask_b32_e64 v10, 0, v10, s[4:5]
	v_exp_f32_e32 v14, v14
	v_mul_f32_e32 v15, 0x3fb8aa3b, v15
	v_add_f32_e32 v162, v9, v162
	v_cndmask_b32_e64 v11, 0, v11, s[6:7]
	v_exp_f32_e32 v15, v15
	v_add_f32_e32 v162, v10, v162
	v_cndmask_b32_e32 v12, 0, v12, vcc
	v_add_f32_e32 v162, v11, v162
	v_cndmask_b32_e64 v13, 0, v13, s[22:23]
	v_add_f32_e32 v162, v12, v162
	v_cndmask_b32_e64 v14, 0, v14, s[28:29]
	v_add_f32_e32 v162, v13, v162
	v_cndmask_b32_e64 v15, 0, v15, s[30:31]
	v_add_f32_e32 v162, v14, v162
	v_add_f32_e32 v162, v15, v162
	s_mov_b64 s[22:23], 0
.LBB0_449:
	s_andn2_b64 vcc, exec, s[22:23]
	s_cbranch_vccnz .LBB0_451
	v_max_f32_e32 v0, v157, v157
	v_max_f32_e32 v1, v156, v156
	v_max_f32_e32 v0, v1, v0
	v_max3_f32 v0, v0, v158, v159
	v_max3_f32 v0, v0, v152, v153
	v_max3_f32 v0, v0, v154, v155
	v_and_b32_e32 v2, 64, v185
	v_max3_f32 v0, v0, v148, v149
	v_xor_b32_e32 v1, 16, v185
	v_add_u32_e32 v2, 64, v2
	v_max3_f32 v0, v0, v150, v151
	v_cmp_lt_i32_e32 vcc, v1, v2
	v_max3_f32 v0, v0, v144, v145
	v_max3_f32 v0, v0, v146, v147
	v_cndmask_b32_e32 v1, v185, v1, vcc
	v_lshlrev_b32_e32 v1, 2, v1
	v_mov_b32_e32 v1, v0
	v_mov_b32_e32 v254, v0
	s_nop 1
	v_permlane16_swap_b32_e32 v1, v254
	s_nop 0
	v_max_f32_e32 v1, v1, v254
	s_waitcnt lgkmcnt(0)
	v_max_f32_e32 v1, v1, v1
	v_max_f32_e32 v0, v0, v1
	v_xor_b32_e32 v1, 32, v185
	v_cmp_lt_i32_e32 vcc, v1, v2
	s_nop 1
	v_cndmask_b32_e32 v1, v185, v1, vcc
	v_lshlrev_b32_e32 v1, 2, v1
	v_mov_b32_e32 v1, v0
	v_mov_b32_e32 v254, v0
	s_nop 1
	v_permlane32_swap_b32_e32 v1, v254
	s_nop 0
	v_max_f32_e32 v1, v1, v254
	s_waitcnt lgkmcnt(0)
	v_max_f32_e32 v1, v1, v1
	v_max_f32_e32 v0, v0, v1
	v_mul_f32_e32 v0, 0x3e000000, v0
	v_max_f32_e32 v1, v180, v180
	v_max_f32_e32 v179, v1, v0
	v_fma_f32 v0, v156, s33, -v179
	v_mul_f32_e32 v0, 0x3fb8aa3b, v0
	v_fma_f32 v1, v157, s33, -v179
	v_exp_f32_e32 v0, v0
	v_mul_f32_e32 v1, 0x3fb8aa3b, v1
	v_fma_f32 v2, v158, s33, -v179
	v_exp_f32_e32 v1, v1
	v_mul_f32_e32 v2, 0x3fb8aa3b, v2
	v_fma_f32 v3, v159, s33, -v179
	v_exp_f32_e32 v2, v2
	v_mul_f32_e32 v3, 0x3fb8aa3b, v3
	v_exp_f32_e32 v3, v3
	v_add_f32_e32 v4, 0, v0
	v_add_f32_e32 v4, v1, v4
	v_add_f32_e32 v4, v2, v4
	v_add_f32_e32 v8, v3, v4
	v_fma_f32 v4, v152, s33, -v179
	v_mul_f32_e32 v4, 0x3fb8aa3b, v4
	v_fma_f32 v5, v153, s33, -v179
	v_exp_f32_e32 v4, v4
	v_mul_f32_e32 v5, 0x3fb8aa3b, v5
	v_fma_f32 v6, v154, s33, -v179
	v_exp_f32_e32 v5, v5
	v_mul_f32_e32 v6, 0x3fb8aa3b, v6
	v_fma_f32 v7, v155, s33, -v179
	v_exp_f32_e32 v6, v6
	v_mul_f32_e32 v7, 0x3fb8aa3b, v7
	v_exp_f32_e32 v7, v7
	v_add_f32_e32 v8, v4, v8
	v_add_f32_e32 v8, v5, v8
	v_add_f32_e32 v8, v6, v8
	v_add_f32_e32 v12, v7, v8
	v_fma_f32 v8, v148, s33, -v179
	v_mul_f32_e32 v8, 0x3fb8aa3b, v8
	v_fma_f32 v9, v149, s33, -v179
	v_exp_f32_e32 v8, v8
	v_mul_f32_e32 v9, 0x3fb8aa3b, v9
	v_fma_f32 v10, v150, s33, -v179
	v_exp_f32_e32 v9, v9
	v_mul_f32_e32 v10, 0x3fb8aa3b, v10
	v_fma_f32 v11, v151, s33, -v179
	v_exp_f32_e32 v10, v10
	v_mul_f32_e32 v11, 0x3fb8aa3b, v11
	v_exp_f32_e32 v11, v11
	v_add_f32_e32 v12, v8, v12
	v_add_f32_e32 v12, v9, v12
	v_add_f32_e32 v12, v10, v12
	v_add_f32_e32 v148, v11, v12
	v_fma_f32 v12, v144, s33, -v179
	v_mul_f32_e32 v12, 0x3fb8aa3b, v12
	v_fma_f32 v13, v145, s33, -v179
	v_exp_f32_e32 v12, v12
	v_mul_f32_e32 v13, 0x3fb8aa3b, v13
	v_fma_f32 v14, v146, s33, -v179
	v_exp_f32_e32 v13, v13
	v_mul_f32_e32 v14, 0x3fb8aa3b, v14
	v_fma_f32 v15, v147, s33, -v179
	v_exp_f32_e32 v14, v14
	v_mul_f32_e32 v15, 0x3fb8aa3b, v15
	v_exp_f32_e32 v15, v15
	v_add_f32_e32 v144, v12, v148
	v_add_f32_e32 v144, v13, v144
	v_add_f32_e32 v144, v14, v144
	v_add_f32_e32 v162, v15, v144
; DI float quad_max(float v) { v = fmaxf(v, __shfl_xor(v, 16)); v = fmaxf(v, __shfl_xor(v, 32)); return v; }
; DI void softmax_tile(f32x4 (&st)[4], const bool (&msk)[4][4], float& m, float& l, f32x4 (&ot)[4]) {
;   float tm = -1e30f;
; #pragma unroll
;   for (int mt = 0; mt < 4; ++mt)
; #pragma unroll
;     for (int j = 0; j < 4; ++j) { float s = st[mt][j] * 0.125f; st[mt][j] = s; if (msk[mt][j]) tm = fmaxf(tm, s); }
;   tm = quad_max(tm);
; DI void win_attn_item(const Params& P, int it, u16* sQ, u16* sKunused, u16* sVunused) {
;     ...
;       st_mma(st, sK, bq[qt], lane);
;       const int tqlo = t0 + 16 * qt;
;       if (kb * 64 + 63 <= tqlo && tqlo + 15 - kb * 64 < 512) softmax_tile_full(st, m[qt], lsum[qt], ot[qt]);
;       else {
;         bool msk[4][4];
; #pragma unroll
;         for (int mt = 0; mt < 4; ++mt)
; #pragma unroll
;           for (int j = 0; j < 4; ++j) { int s = kb * 64 + 16 * mt + 4 * quad + j; int df = tq[qt] - s; msk[mt][j] = (df >= 0) && (df < 512); }
;         softmax_tile(st, msk, m[qt], lsum[qt], ot[qt]);
;       }
;       pv_mma(ot[qt], sVt, st, lane);
.LBB0_451:
	v_sub_f32_e32 v144, v180, v179
	v_mul_f32_e32 v144, 0x3fb8aa3b, v144
	v_exp_f32_e32 v148, v144
	v_cvt_pk_bf16_f32 v0, v0, v1
	v_cvt_pk_bf16_f32 v1, v2, v3
	v_cvt_pk_bf16_f32 v2, v4, v5
	v_pk_mul_f32 v[46:47], v[46:47], v[148:149] op_sel_hi:[1,0]
	v_pk_mul_f32 v[44:45], v[44:45], v[148:149] op_sel_hi:[1,0]
	v_cvt_pk_bf16_f32 v3, v6, v7
	v_pk_mul_f32 v[42:43], v[42:43], v[148:149] op_sel_hi:[1,0]
	v_pk_mul_f32 v[40:41], v[40:41], v[148:149] op_sel_hi:[1,0]
	v_pk_mul_f32 v[38:39], v[38:39], v[148:149] op_sel_hi:[1,0]
	v_pk_mul_f32 v[36:37], v[36:37], v[148:149] op_sel_hi:[1,0]
	v_pk_mul_f32 v[34:35], v[34:35], v[148:149] op_sel_hi:[1,0]
	v_pk_mul_f32 v[32:33], v[32:33], v[148:149] op_sel_hi:[1,0]
	v_mfma_f32_16x16x32_bf16 v[4:7], v[108:111], v[0:3], v[44:47]
	v_cvt_pk_bf16_f32 v8, v8, v9
	v_cvt_pk_bf16_f32 v9, v10, v11
	v_cvt_pk_bf16_f32 v10, v12, v13
	v_mfma_f32_16x16x32_bf16 v[40:43], v[104:107], v[0:3], v[40:43]
	v_cvt_pk_bf16_f32 v11, v14, v15
	s_cmp_le_u32 s49, s45
	s_cselect_b64 s[0:1], -1, 0
	v_mfma_f32_16x16x32_bf16 v[36:39], v[100:103], v[0:3], v[36:39]
	s_cmp_gt_i32 s50, s48
	s_cselect_b64 s[4:5], -1, 0
	s_and_b64 s[4:5], s[0:1], s[4:5]
	v_mfma_f32_16x16x32_bf16 v[0:3], v[96:99], v[0:3], v[32:35]
	s_mov_b64 s[0:1], -1
	s_and_b64 vcc, exec, s[4:5]
	v_mfma_f32_16x16x32_bf16 v[32:35], v[84:87], v[8:11], v[0:3]
	v_mfma_f32_16x16x32_bf16 v[0:3], v[116:119], v[56:59], 0
	v_mfma_f32_16x16x32_bf16 v[144:147], v[120:123], v[60:63], v[0:3]
	v_mfma_f32_16x16x32_bf16 v[0:3], v[124:127], v[56:59], 0
	v_mfma_f32_16x16x32_bf16 v[120:123], v[128:131], v[60:63], v[0:3]
	v_mfma_f32_16x16x32_bf16 v[0:3], v[132:135], v[56:59], 0
	v_mfma_f32_16x16x32_bf16 v[116:119], v[112:115], v[60:63], v[0:3]
	v_mfma_f32_16x16x32_bf16 v[112:115], v[140:143], v[56:59], 0
	v_mfma_f32_16x16x32_bf16 v[44:47], v[80:83], v[8:11], v[4:7]
	v_mfma_f32_16x16x32_bf16 v[40:43], v[92:95], v[8:11], v[40:43]
	v_mfma_f32_16x16x32_bf16 v[36:39], v[88:91], v[8:11], v[36:39]
	v_mfma_f32_16x16x32_bf16 v[112:115], v[136:139], v[60:63], v[112:115]
	s_cbranch_vccnz .LBB0_453
	s_nop 0
	v_add_u32_e32 v0, 33, v174
	v_mul_f32_e32 v5, 0x3e000000, v144
	s_movk_i32 s30, 0x200
	v_max_f32_e32 v5, 0xf149f2ca, v5
	v_cmp_gt_u32_e64 s[4:5], s30, v0
	v_add_u32_e32 v1, 0xffffffb1, v218
	s_movk_i32 s0, 0xfdff
	v_cndmask_b32_e64 v0, v186, v5, s[4:5]
	v_mul_f32_e32 v5, 0x3e000000, v145
	v_max_f32_e32 v5, v0, v5
	v_cmp_lt_u32_e64 s[10:11], s0, v1
	v_add_u32_e32 v2, 31, v174
	v_mul_f32_e32 v1, 0x3e000000, v146
	v_cndmask_b32_e64 v0, v0, v5, s[10:11]
	v_max_f32_e32 v1, v0, v1
	v_cmp_gt_u32_e64 s[18:19], s30, v2
	v_add_u32_e32 v3, 30, v174
	v_cmp_gt_u32_e64 s[20:21], s30, v3
	v_cndmask_b32_e64 v0, v0, v1, s[18:19]
	v_mul_f32_e32 v1, 0x3e000000, v147
	v_max_f32_e32 v1, v0, v1
	v_cndmask_b32_e64 v0, v0, v1, s[20:21]
	v_mul_f32_e32 v1, 0x3e000000, v120
	v_max_f32_e32 v1, v0, v1
	v_cmp_gt_u32_e32 vcc, s30, v217
	v_add_u32_e32 v4, 16, v174
	v_cmp_gt_u32_e64 s[6:7], s30, v4
	v_cndmask_b32_e32 v0, v0, v1, vcc
	v_mul_f32_e32 v1, 0x3e000000, v121
	v_max_f32_e32 v2, v0, v0
	v_max_f32_e32 v1, v2, v1
	v_cndmask_b32_e64 v0, v0, v1, s[6:7]
	v_mul_f32_e32 v1, 0x3e000000, v122
	v_max_f32_e32 v2, v0, v0
	v_max_f32_e32 v1, v2, v1
	v_cmp_gt_u32_e64 s[14:15], s30, v216
	v_cmp_gt_u32_e64 s[22:23], s30, v215
	v_cmp_gt_u32_e64 s[0:1], s30, v214
	v_cndmask_b32_e64 v0, v0, v1, s[14:15]
	v_mul_f32_e32 v1, 0x3e000000, v123
	v_max_f32_e32 v2, v0, v0
	v_max_f32_e32 v1, v2, v1
	v_cndmask_b32_e64 v0, v0, v1, s[22:23]
	v_mul_f32_e32 v1, 0x3e000000, v116
	v_max_f32_e32 v2, v0, v0
	v_max_f32_e32 v1, v2, v1
	v_cndmask_b32_e64 v0, v0, v1, s[0:1]
	v_mul_f32_e32 v1, 0x3e000000, v117
	v_max_f32_e32 v2, v0, v0
	v_max_f32_e32 v1, v2, v1
	v_cmp_gt_u32_e64 s[8:9], s30, v174
	v_cmp_gt_u32_e64 s[24:25], s30, v213
	v_cmp_gt_u32_e64 s[26:27], s30, v212
	v_cndmask_b32_e64 v0, v0, v1, s[8:9]
	v_mul_f32_e32 v1, 0x3e000000, v118
	v_max_f32_e32 v2, v0, v0
	v_max_f32_e32 v1, v2, v1
	v_cndmask_b32_e64 v0, v0, v1, s[24:25]
	v_mul_f32_e32 v1, 0x3e000000, v119
	v_max_f32_e32 v2, v0, v0
	v_max_f32_e32 v1, v2, v1
	v_cndmask_b32_e64 v0, v0, v1, s[26:27]
	v_mul_f32_e32 v1, 0x3e000000, v112
	v_max_f32_e32 v2, v0, v0
	v_max_f32_e32 v1, v2, v1
	v_cmp_gt_u32_e64 s[16:17], s30, v211
	v_cmp_gt_u32_e64 s[12:13], s30, v210
	v_cmp_gt_u32_e64 s[28:29], s30, v209
	v_cndmask_b32_e64 v0, v0, v1, s[16:17]
	v_mul_f32_e32 v1, 0x3e000000, v113
	v_max_f32_e32 v2, v0, v0
	v_max_f32_e32 v1, v2, v1
	v_cndmask_b32_e64 v0, v0, v1, s[12:13]
	v_mul_f32_e32 v1, 0x3e000000, v114
	v_max_f32_e32 v2, v0, v0
	v_max_f32_e32 v1, v2, v1
	v_cndmask_b32_e64 v0, v0, v1, s[28:29]
	v_mul_f32_e32 v1, 0x3e000000, v115
	v_max_f32_e32 v2, v0, v0
	v_max_f32_e32 v1, v2, v1
	v_cmp_gt_u32_e64 s[30:31], s30, v181
	v_and_b32_e32 v2, 64, v185
	v_add_u32_e32 v2, 64, v2
	v_cndmask_b32_e64 v0, v0, v1, s[30:31]
	v_xor_b32_e32 v1, 16, v185
	v_cmp_lt_i32_e64 s[34:35], v1, v2
	s_nop 1
	v_cndmask_b32_e64 v1, v185, v1, s[34:35]
	v_lshlrev_b32_e32 v1, 2, v1
	v_mov_b32_e32 v1, v0
	v_mov_b32_e32 v254, v0
	s_nop 1
	v_permlane16_swap_b32_e32 v1, v254
	s_nop 0
	v_max_f32_e32 v1, v1, v254
	v_max_f32_e32 v0, v0, v0
	s_waitcnt lgkmcnt(0)
	v_max_f32_e32 v1, v1, v1
	v_max_f32_e32 v0, v0, v1
	v_xor_b32_e32 v1, 32, v185
	v_cmp_lt_i32_e64 s[34:35], v1, v2
	s_nop 1
	v_cndmask_b32_e64 v1, v185, v1, s[34:35]
	v_lshlrev_b32_e32 v1, 2, v1
	v_mov_b32_e32 v1, v0
	v_mov_b32_e32 v254, v0
	s_nop 1
	v_permlane32_swap_b32_e32 v1, v254
	s_nop 0
	v_max_f32_e32 v1, v1, v254
	s_waitcnt lgkmcnt(0)
; DI float quad_max(float v) { v = fmaxf(v, __shfl_xor(v, 16)); v = fmaxf(v, __shfl_xor(v, 32)); return v; }
; DI void softmax_tile(f32x4 (&st)[4], const bool (&msk)[4][4], float& m, float& l, f32x4 (&ot)[4]) {
;   float tm = -1e30f;
; #pragma unroll
;   for (int mt = 0; mt < 4; ++mt)
; #pragma unroll
;     for (int j = 0; j < 4; ++j) { float s = st[mt][j] * 0.125f; st[mt][j] = s; if (msk[mt][j]) tm = fmaxf(tm, s); }
;   tm = quad_max(tm);
;   float mn = fmaxf(m, tm);
;   float alpha = __expf(m - mn);
;   float ps = 0.f;
; #pragma unroll
;   for (int mt = 0; mt < 4; ++mt)
; #pragma unroll
;     for (int j = 0; j < 4; ++j) { float p = msk[mt][j] ? __expf(st[mt][j] - mn) : 0.f; st[mt][j] = p; ps += p; }
;   l = l * alpha + ps;
; DI void softmax_tile_full(f32x4 (&st)[4], float& m, float& l, f32x4 (&ot)[4]) {
;   float tm = st[0][0];
; #pragma unroll
;   for (int mt = 0; mt < 4; ++mt)
; #pragma unroll
;     for (int j = 0; j < 4; ++j) tm = fmaxf(tm, st[mt][j]);
;   tm = quad_max(tm) * 0.125f;
;   const float mn = fmaxf(m, tm);
;   const float alpha = __expf(m - mn);
;   float ps = 0.f;
; #pragma unroll
;   for (int mt = 0; mt < 4; ++mt)
; #pragma unroll
;     for (int j = 0; j < 4; ++j) { const float p = __expf(st[mt][j] * 0.125f - mn); st[mt][j] = p; ps += p; }
	v_max3_f32 v125, v177, v0, v1
	v_fma_f32 v0, v144, s33, -v125
	v_mul_f32_e32 v0, 0x3fb8aa3b, v0
	v_fma_f32 v1, v145, s33, -v125
	v_exp_f32_e32 v0, v0
	v_mul_f32_e32 v1, 0x3fb8aa3b, v1
	v_fma_f32 v2, v146, s33, -v125
	v_exp_f32_e32 v1, v1
	v_mul_f32_e32 v2, 0x3fb8aa3b, v2
	v_fma_f32 v3, v147, s33, -v125
	v_exp_f32_e32 v2, v2
	v_mul_f32_e32 v3, 0x3fb8aa3b, v3
	v_fma_f32 v4, v120, s33, -v125
	v_exp_f32_e32 v3, v3
	v_mul_f32_e32 v4, 0x3fb8aa3b, v4
	v_fma_f32 v5, v121, s33, -v125
	v_cndmask_b32_e64 v0, 0, v0, s[4:5]
	v_exp_f32_e32 v4, v4
	v_mul_f32_e32 v5, 0x3fb8aa3b, v5
	v_fma_f32 v6, v122, s33, -v125
	v_cndmask_b32_e64 v1, 0, v1, s[10:11]
	v_exp_f32_e32 v5, v5
	v_mul_f32_e32 v6, 0x3fb8aa3b, v6
	v_fma_f32 v7, v123, s33, -v125
	v_add_f32_e32 v124, 0, v0
	v_cndmask_b32_e64 v2, 0, v2, s[18:19]
	v_exp_f32_e32 v6, v6
	v_mul_f32_e32 v7, 0x3fb8aa3b, v7
	v_fma_f32 v8, v116, s33, -v125
	v_add_f32_e32 v124, v1, v124
	v_cndmask_b32_e64 v3, 0, v3, s[20:21]
	v_exp_f32_e32 v7, v7
	v_mul_f32_e32 v8, 0x3fb8aa3b, v8
	v_fma_f32 v9, v117, s33, -v125
	v_add_f32_e32 v124, v2, v124
	v_cndmask_b32_e32 v4, 0, v4, vcc
	v_exp_f32_e32 v8, v8
	v_mul_f32_e32 v9, 0x3fb8aa3b, v9
	v_fma_f32 v10, v118, s33, -v125
	v_add_f32_e32 v124, v3, v124
	v_cndmask_b32_e64 v5, 0, v5, s[6:7]
	v_exp_f32_e32 v9, v9
	v_mul_f32_e32 v10, 0x3fb8aa3b, v10
	v_fma_f32 v11, v119, s33, -v125
	v_add_f32_e32 v124, v4, v124
	v_cndmask_b32_e64 v6, 0, v6, s[14:15]
	v_exp_f32_e32 v10, v10
	v_mul_f32_e32 v11, 0x3fb8aa3b, v11
	v_fma_f32 v12, v112, s33, -v125
	v_add_f32_e32 v124, v5, v124
	v_cndmask_b32_e64 v7, 0, v7, s[22:23]
	v_exp_f32_e32 v11, v11
	v_mul_f32_e32 v12, 0x3fb8aa3b, v12
	v_fma_f32 v13, v113, s33, -v125
	v_add_f32_e32 v124, v6, v124
	v_cndmask_b32_e64 v8, 0, v8, s[0:1]
	v_exp_f32_e32 v12, v12
	v_mul_f32_e32 v13, 0x3fb8aa3b, v13
	v_fma_f32 v14, v114, s33, -v125
	v_add_f32_e32 v124, v7, v124
	v_cndmask_b32_e64 v9, 0, v9, s[8:9]
	v_exp_f32_e32 v13, v13
	v_mul_f32_e32 v14, 0x3fb8aa3b, v14
	v_fma_f32 v15, v115, s33, -v125
	v_add_f32_e32 v124, v8, v124
	v_cndmask_b32_e64 v10, 0, v10, s[24:25]
	v_exp_f32_e32 v14, v14
	v_mul_f32_e32 v15, 0x3fb8aa3b, v15
	v_add_f32_e32 v124, v9, v124
	v_cndmask_b32_e64 v11, 0, v11, s[26:27]
	v_exp_f32_e32 v15, v15
	v_add_f32_e32 v124, v10, v124
	v_cndmask_b32_e64 v12, 0, v12, s[16:17]
	v_add_f32_e32 v124, v11, v124
	v_cndmask_b32_e64 v13, 0, v13, s[12:13]
	v_add_f32_e32 v124, v12, v124
	v_cndmask_b32_e64 v14, 0, v14, s[28:29]
	v_add_f32_e32 v124, v13, v124
	v_cndmask_b32_e64 v15, 0, v15, s[30:31]
	v_add_f32_e32 v124, v14, v124
	v_add_f32_e32 v124, v15, v124
	s_mov_b64 s[0:1], 0
.LBB0_453:
	s_andn2_b64 vcc, exec, s[0:1]
	s_cbranch_vccnz .LBB0_455
	v_max_f32_e32 v0, v145, v145
	v_max_f32_e32 v1, v144, v144
	v_max_f32_e32 v0, v1, v0
	v_max3_f32 v0, v0, v146, v147
	v_max3_f32 v0, v0, v120, v121
	v_max3_f32 v0, v0, v122, v123
	v_and_b32_e32 v2, 64, v185
	v_max3_f32 v0, v0, v116, v117
	v_xor_b32_e32 v1, 16, v185
	v_add_u32_e32 v2, 64, v2
	v_max3_f32 v0, v0, v118, v119
	v_cmp_lt_i32_e32 vcc, v1, v2
	v_max3_f32 v0, v0, v112, v113
	v_max3_f32 v0, v0, v114, v115
	v_cndmask_b32_e32 v1, v185, v1, vcc
	v_lshlrev_b32_e32 v1, 2, v1
	v_mov_b32_e32 v1, v0
	v_mov_b32_e32 v254, v0
	s_nop 1
	v_permlane16_swap_b32_e32 v1, v254
	s_nop 0
	v_max_f32_e32 v1, v1, v254
	s_waitcnt lgkmcnt(0)
	v_max_f32_e32 v1, v1, v1
	v_max_f32_e32 v0, v0, v1
	v_xor_b32_e32 v1, 32, v185
	v_cmp_lt_i32_e32 vcc, v1, v2
	s_nop 1
	v_cndmask_b32_e32 v1, v185, v1, vcc
	v_lshlrev_b32_e32 v1, 2, v1
	v_mov_b32_e32 v1, v0
	v_mov_b32_e32 v254, v0
	s_nop 1
	v_permlane32_swap_b32_e32 v1, v254
	s_nop 0
	v_max_f32_e32 v1, v1, v254
	s_waitcnt lgkmcnt(0)
	v_max_f32_e32 v1, v1, v1
	v_max_f32_e32 v0, v0, v1
	v_mul_f32_e32 v0, 0x3e000000, v0
	v_max_f32_e32 v1, v177, v177
	v_max_f32_e32 v125, v1, v0
	v_fma_f32 v0, v144, s33, -v125
	v_mul_f32_e32 v0, 0x3fb8aa3b, v0
	v_fma_f32 v1, v145, s33, -v125
	v_exp_f32_e32 v0, v0
	v_mul_f32_e32 v1, 0x3fb8aa3b, v1
	v_fma_f32 v2, v146, s33, -v125
	v_exp_f32_e32 v1, v1
	v_mul_f32_e32 v2, 0x3fb8aa3b, v2
	v_fma_f32 v3, v147, s33, -v125
	v_exp_f32_e32 v2, v2
	v_mul_f32_e32 v3, 0x3fb8aa3b, v3
	v_exp_f32_e32 v3, v3
	v_add_f32_e32 v4, 0, v0
	v_add_f32_e32 v4, v1, v4
	v_add_f32_e32 v4, v2, v4
	v_add_f32_e32 v8, v3, v4
	v_fma_f32 v4, v120, s33, -v125
	v_mul_f32_e32 v4, 0x3fb8aa3b, v4
	v_fma_f32 v5, v121, s33, -v125
	v_exp_f32_e32 v4, v4
	v_mul_f32_e32 v5, 0x3fb8aa3b, v5
	v_fma_f32 v6, v122, s33, -v125
	v_exp_f32_e32 v5, v5
	v_mul_f32_e32 v6, 0x3fb8aa3b, v6
	v_fma_f32 v7, v123, s33, -v125
	v_exp_f32_e32 v6, v6
	v_mul_f32_e32 v7, 0x3fb8aa3b, v7
	v_exp_f32_e32 v7, v7
	v_add_f32_e32 v8, v4, v8
	v_add_f32_e32 v8, v5, v8
	v_add_f32_e32 v8, v6, v8
	v_add_f32_e32 v12, v7, v8
	v_fma_f32 v8, v116, s33, -v125
	v_mul_f32_e32 v8, 0x3fb8aa3b, v8
	v_fma_f32 v9, v117, s33, -v125
	v_exp_f32_e32 v8, v8
	v_mul_f32_e32 v9, 0x3fb8aa3b, v9
	v_fma_f32 v10, v118, s33, -v125
	v_exp_f32_e32 v9, v9
	v_mul_f32_e32 v10, 0x3fb8aa3b, v10
	v_fma_f32 v11, v119, s33, -v125
	v_exp_f32_e32 v10, v10
	v_mul_f32_e32 v11, 0x3fb8aa3b, v11
	v_exp_f32_e32 v11, v11
	v_add_f32_e32 v12, v8, v12
	v_add_f32_e32 v12, v9, v12
	v_add_f32_e32 v12, v10, v12
	v_add_f32_e32 v116, v11, v12
	v_fma_f32 v12, v112, s33, -v125
	v_mul_f32_e32 v12, 0x3fb8aa3b, v12
	v_fma_f32 v13, v113, s33, -v125
	v_exp_f32_e32 v12, v12
	v_mul_f32_e32 v13, 0x3fb8aa3b, v13
	v_fma_f32 v14, v114, s33, -v125
	v_exp_f32_e32 v13, v13
	v_mul_f32_e32 v14, 0x3fb8aa3b, v14
	v_fma_f32 v15, v115, s33, -v125
	v_exp_f32_e32 v14, v14
	v_mul_f32_e32 v15, 0x3fb8aa3b, v15
	v_exp_f32_e32 v15, v15
	v_add_f32_e32 v112, v12, v116
	v_add_f32_e32 v112, v13, v112
	v_add_f32_e32 v112, v14, v112
	v_add_f32_e32 v124, v15, v112
